# dt columns of in-proj via a mini GEMM (removes the 7th straggler round)
# speedup vs baseline: 1.0430x; 1.0001x over previous
.LBB0_200:
	s_cmp_gt_i32 s60, 2
	s_waitcnt lgkmcnt(0)
	s_cselect_b64 s[2:3], -1, 0
	s_cmp_lt_i32 s61, 2
	s_cselect_b64 s[4:5], -1, 0
	s_or_b64 s[2:3], s[2:3], s[4:5]
	s_and_b64 vcc, exec, s[2:3]
	s_cbranch_vccnz .LBB0_472
	s_mov_b64 s[14:15], s[0:1]
	s_cmpk_gt_i32 s58, 0xc3f
	s_cbranch_scc1 .LBB0_418
	s_load_dwordx2 s[16:17], s[14:15], 0xe0
	s_load_dword s3, s[0:1], 0xf0
	v_lshrrev_b32_e32 v9, 3, v162
	v_lshlrev_b32_e32 v0, 3, v162
	v_and_b32_e32 v0, 56, v0
	s_waitcnt lgkmcnt(0)
	s_add_u32 s18, s16, 0x8b7a100
	s_addc_u32 s19, s17, 0
	v_mov_b32_e32 v99, 0
	v_lshlrev_b32_e32 v98, 11, v9
	v_lshl_add_u64 v[4:5], s[18:19], 0, v[98:99]
	v_lshlrev_b32_e32 v6, 1, v0
	v_mov_b32_e32 v7, v99
	v_xor_b32_e32 v10, v163, v162
	v_lshl_add_u64 v[100:101], v[4:5], 0, v[6:7]
	v_lshl_add_u64 v[4:5], s[16:17], 0, v[98:99]
	v_lshl_add_u64 v[102:103], v[4:5], 0, v[6:7]
	v_lshlrev_b32_e32 v5, 4, v10
	v_and_b32_e32 v96, 15, v162
	v_bfe_u32 v4, v162, 1, 3
	v_and_b32_e32 v5, 0x70, v5
	v_bfe_u32 v1, v162, 6, 1
	v_lshrrev_b32_e32 v3, 7, v162
	v_bitop3_b32 v4, v163, v4, 3 bitop3:0x6c
	v_lshl_or_b32 v160, v9, 7, v5
	v_lshlrev_b32_e32 v5, 7, v96
	v_lshl_or_b32 v6, v3, 13, v5
	v_lshl_or_b32 v5, v1, 13, v5
	v_lshlrev_b32_e32 v4, 4, v4
	v_or_b32_e32 v161, v6, v4
	v_or_b32_e32 v165, v5, v4
	v_xor_b32_e32 v4, 64, v4
	v_or_b32_e32 v166, v6, v4
	v_or_b32_e32 v167, v5, v4
	v_lshlrev_b32_e32 v4, 2, v96
	v_mov_b32_e32 v5, v99
	v_lshl_add_u64 v[4:5], s[16:17], 0, v[4:5]
	s_mov_b64 s[6:7], 0x1237a100
	v_lshl_add_u64 v[104:105], v[4:5], 0, s[6:7]
	s_mov_b64 s[6:7], 0x1237a140
	v_lshl_add_u64 v[106:107], v[4:5], 0, s[6:7]
	v_lshlrev_b32_e32 v4, 7, v1
	v_mov_b32_e32 v5, v99
	v_lshl_add_u64 v[4:5], s[16:17], 0, v[4:5]
	s_mov_b64 s[6:7], 0xdb7a100
	s_add_u32 s22, s16, 0xef7a100
	v_lshl_add_u64 v[108:109], v[4:5], 0, s[6:7]
	s_mov_b64 s[6:7], 0xe37a100
	v_lshlrev_b32_e32 v169, 6, v1
	v_cmp_eq_u32_e64 s[4:5], 0, v1
	s_addc_u32 s23, s17, 0
	v_lshl_add_u64 v[110:111], v[4:5], 0, s[6:7]
	v_lshlrev_b32_e32 v4, 1, v96
	v_mov_b32_e32 v5, v99
	v_and_b32_e32 v1, 7, v162
	s_add_u32 s24, s16, 0x6b00000
	v_lshl_add_u64 v[4:5], s[16:17], 0, v[4:5]
	s_mov_b64 s[6:7], 0x9b7a100
	v_lshl_or_b32 v98, v1, 4, v98
	s_addc_u32 s25, s17, 0
	v_lshl_add_u64 v[112:113], v[4:5], 0, s[6:7]
	v_lshl_add_u64 v[4:5], s[16:17], 0, v[98:99]
	s_mov_b64 s[6:7], 0x200
	v_bfe_u32 v8, v162, 4, 2
	v_lshlrev_b32_e32 v2, 10, v9
	v_lshlrev_b32_e32 v3, 6, v3
	s_add_u32 s26, s16, 0xcb7a100
	v_lshl_add_u64 v[114:115], v[4:5], 0, s[6:7]
	s_mov_b64 s[6:7], 0x8b7a300
	v_lshl_or_b32 v168, v8, 2, v3
	s_mov_b32 s21, 0
	v_or_b32_e32 v170, v169, v96
	s_addc_u32 s27, s17, 0
	s_lshl_b32 s66, s58, 1
	s_lshl_b32 s67, s3, 1
	v_lshl_add_u64 v[116:117], v[4:5], 0, s[6:7]
	s_lshl_b32 s68, s58, 7
	s_lshl_b32 s69, s3, 7
	s_mov_b64 s[8:9], 0
	s_movk_i32 s70, 0xff80
	s_mov_b32 s71, 0x10000
	s_mov_b64 s[28:29], 0x100
	s_mov_b64 s[30:31], 0x10000
	s_mov_b64 s[34:35], 0x10100
	s_mov_b64 s[36:37], 0x20000
	s_mov_b64 s[38:39], 0x20100
	s_mov_b64 s[40:41], 0x30000
	s_mov_b64 s[42:43], 0x30100
	v_lshlrev_b32_e32 v118, 1, v2
	v_mov_b32_e32 v119, v99
	v_lshlrev_b32_e32 v120, 1, v0
	v_mov_b32_e32 v121, v99
	s_mov_b64 s[44:45], 0x780
	s_mov_b32 s72, 0x3fff80
	s_mov_b32 s73, 0xf77a000
	s_mov_b32 s74, 0xf786000
	s_mov_b64 s[46:47], 0xf79e500
	s_movk_i32 s75, 0xf400
	s_movk_i32 s76, 0x7e00
	s_mov_b64 s[48:49], 0x2000000
	s_movk_i32 s77, 0xf0
	s_movk_i32 s78, 0xc0
	s_movk_i32 s79, 0x600
	s_movk_i32 s80, 0x200
	s_movk_i32 s81, 0x3d0
	s_movk_i32 s82, 0x3e0
	s_movk_i32 s83, 0x3f0
	s_movk_i32 s59, 0x3c0
	s_mov_b32 s86, 0xab89000
	s_mov_b32 s87, 0xab8a000
	s_mov_b32 s88, 0xab8b000
	s_mov_b32 s89, 0xab8c000
	s_mov_b32 s90, 0xab99000
	s_mov_b32 s91, 0xab9a000
	s_mov_b32 s92, 0xab9b000
	s_mov_b32 s93, 0xab9c000
	s_mov_b32 s94, 0xaba9000
	s_mov_b32 s95, 0xabaa000
	s_mov_b32 s96, 0xabab000
	s_mov_b32 s97, 0xabac000
	s_mov_b64 s[50:51], 0x60
	s_mov_b32 s2, s58
	v_and_b32_e32 v240, 63, v162
	v_lshrrev_b32_e32 v247, 6, v162
	v_lshrrev_b32_e32 v242, 3, v240
	v_lshl_add_u32 v242, v247, 5, v242
	v_and_b32_e32 v243, 7, v240
	v_lshrrev_b32_e32 v244, 4, v240
	v_xor_b32_e32 v243, v243, v244
	v_lshlrev_b32_e32 v243, 4, v243
	v_mov_b32_e32 v241, 0x800
	v_mad_u32_u24 v248, v242, v241, v243
	v_xor_b32_e32 v249, 64, v248
	v_add_u32_e32 v249, 0x4000, v249
	v_add_u32_e32 v250, 0x8000, v248
	v_xor_b32_e32 v251, 64, v248
	v_add_u32_e32 v251, 0xc000, v251
	v_and_b32_e32 v241, 15, v240
	v_lshrrev_b32_e32 v242, 1, v241
	v_xor_b32_e32 v242, v242, v244
	v_lshlrev_b32_e32 v242, 4, v242
	v_lshl_or_b32 v242, v241, 7, v242
	v_lshrrev_b32_e32 v243, 1, v247
	v_lshl_or_b32 v252, v243, 13, v242
	v_xor_b32_e32 v253, 64, v252
	v_and_b32_e32 v243, 1, v247
	v_lshl_or_b32 v254, v243, 13, v242
	v_xor_b32_e32 v255, 64, v254
	s_load_dwordx2 s[6:7], s[0:1], 0xe0
	s_load_dword s20, s[0:1], 0xf0
	v_and_b32_e32 v155, 63, v162
	v_lshrrev_b32_e32 v154, 6, v162
	v_and_b32_e32 v152, 15, v155
	v_lshrrev_b32_e32 v153, 4, v155
	v_lshlrev_b32_e32 v153, 4, v153
	v_lshl_add_u32 v153, v154, 9, v153
	v_lshl_add_u32 v152, v152, 11, v153
	s_waitcnt lgkmcnt(0)
	s_mov_b32 s32, s58
.Ldt2_rb:
	s_cmp_lt_u32 s32, 0x200
	s_cbranch_scc0 .Ldt2_end
	s_lshl_b32 s10, s32, 15
	s_add_u32 s10, s10, 0x8b7a100
	s_add_u32 s10, s6, s10
	s_addc_u32 s11, s7, 0
	s_add_u32 s12, s6, 0xc00000
	s_addc_u32 s13, s7, 0
	global_load_dwordx4 v[0:3], v152, s[10:11] offset:0
	global_load_dwordx4 v[4:7], v152, s[12:13] offset:0
	global_load_dwordx4 v[8:11], v152, s[10:11] offset:64
	global_load_dwordx4 v[12:15], v152, s[12:13] offset:64
	global_load_dwordx4 v[16:19], v152, s[10:11] offset:128
	global_load_dwordx4 v[20:23], v152, s[12:13] offset:128
	global_load_dwordx4 v[24:27], v152, s[10:11] offset:192
	global_load_dwordx4 v[28:31], v152, s[12:13] offset:192
	global_load_dwordx4 v[32:35], v152, s[10:11] offset:256
	global_load_dwordx4 v[36:39], v152, s[12:13] offset:256
	global_load_dwordx4 v[40:43], v152, s[10:11] offset:320
	global_load_dwordx4 v[44:47], v152, s[12:13] offset:320
	global_load_dwordx4 v[48:51], v152, s[10:11] offset:384
	global_load_dwordx4 v[52:55], v152, s[12:13] offset:384
	global_load_dwordx4 v[56:59], v152, s[10:11] offset:448
	global_load_dwordx4 v[60:63], v152, s[12:13] offset:448
	s_add_u32 s12, s12, 0x8000
	s_addc_u32 s13, s13, 0
	global_load_dwordx4 v[80:83], v152, s[12:13] offset:0
	global_load_dwordx4 v[84:87], v152, s[12:13] offset:64
	global_load_dwordx4 v[88:91], v152, s[12:13] offset:128
	global_load_dwordx4 v[92:95], v152, s[12:13] offset:192
	global_load_dwordx4 v[124:127], v152, s[12:13] offset:256
	global_load_dwordx4 v[132:135], v152, s[12:13] offset:320
	global_load_dwordx4 v[136:139], v152, s[12:13] offset:384
	global_load_dwordx4 v[140:143], v152, s[12:13] offset:448
	v_mov_b32_e32 v144, 0
	v_mov_b32_e32 v145, 0
	v_mov_b32_e32 v146, 0
	v_mov_b32_e32 v147, 0
	v_mov_b32_e32 v148, 0
	v_mov_b32_e32 v149, 0
	v_mov_b32_e32 v150, 0
	v_mov_b32_e32 v151, 0
	s_waitcnt vmcnt(22)
	v_mfma_f32_16x16x32_bf16 v[144:147], v[0:3], v[4:7], v[144:147]
	s_waitcnt vmcnt(20)
	v_mfma_f32_16x16x32_bf16 v[144:147], v[8:11], v[12:15], v[144:147]
	s_waitcnt vmcnt(18)
	v_mfma_f32_16x16x32_bf16 v[144:147], v[16:19], v[20:23], v[144:147]
	s_waitcnt vmcnt(16)
	v_mfma_f32_16x16x32_bf16 v[144:147], v[24:27], v[28:31], v[144:147]
	s_waitcnt vmcnt(14)
	v_mfma_f32_16x16x32_bf16 v[144:147], v[32:35], v[36:39], v[144:147]
	s_waitcnt vmcnt(12)
	v_mfma_f32_16x16x32_bf16 v[144:147], v[40:43], v[44:47], v[144:147]
	s_waitcnt vmcnt(10)
	v_mfma_f32_16x16x32_bf16 v[144:147], v[48:51], v[52:55], v[144:147]
	s_waitcnt vmcnt(8)
	v_mfma_f32_16x16x32_bf16 v[144:147], v[56:59], v[60:63], v[144:147]
	s_waitcnt vmcnt(7)
	v_mfma_f32_16x16x32_bf16 v[148:151], v[0:3], v[80:83], v[148:151]
	s_waitcnt vmcnt(6)
	v_mfma_f32_16x16x32_bf16 v[148:151], v[8:11], v[84:87], v[148:151]
	s_waitcnt vmcnt(5)
	v_mfma_f32_16x16x32_bf16 v[148:151], v[16:19], v[88:91], v[148:151]
	s_waitcnt vmcnt(4)
	v_mfma_f32_16x16x32_bf16 v[148:151], v[24:27], v[92:95], v[148:151]
	s_waitcnt vmcnt(3)
	v_mfma_f32_16x16x32_bf16 v[148:151], v[32:35], v[124:127], v[148:151]
	s_waitcnt vmcnt(2)
	v_mfma_f32_16x16x32_bf16 v[148:151], v[40:43], v[132:135], v[148:151]
	s_waitcnt vmcnt(1)
	v_mfma_f32_16x16x32_bf16 v[148:151], v[48:51], v[136:139], v[148:151]
	s_waitcnt vmcnt(0)
	v_mfma_f32_16x16x32_bf16 v[148:151], v[56:59], v[140:143], v[148:151]
	s_nop 7
	s_nop 1
	v_lshlrev_b32_e32 v153, 2, v155
	v_lshl_add_u32 v153, v154, 11, v153
	s_barrier
	ds_write_b32 v153, v144 offset:0
	ds_write_b32 v153, v145 offset:256
	ds_write_b32 v153, v146 offset:512
	ds_write_b32 v153, v147 offset:768
	ds_write_b32 v153, v148 offset:1024
	ds_write_b32 v153, v149 offset:1280
	ds_write_b32 v153, v150 offset:1536
	ds_write_b32 v153, v151 offset:1792
	s_waitcnt lgkmcnt(0)
	s_barrier
	v_cmp_eq_u32_e32 vcc, 0, v154
	s_and_saveexec_b64 s[54:55], vcc
	s_cbranch_execz .Ldt2_skip
	ds_read_b32 v0, v153 offset:2048
	ds_read_b32 v1, v153 offset:2304
	ds_read_b32 v2, v153 offset:2560
	ds_read_b32 v3, v153 offset:2816
	ds_read_b32 v4, v153 offset:3072
	ds_read_b32 v5, v153 offset:3328
	ds_read_b32 v6, v153 offset:3584
	ds_read_b32 v7, v153 offset:3840
	ds_read_b32 v8, v153 offset:4096
	ds_read_b32 v9, v153 offset:4352
	ds_read_b32 v10, v153 offset:4608
	ds_read_b32 v11, v153 offset:4864
	ds_read_b32 v12, v153 offset:5120
	ds_read_b32 v13, v153 offset:5376
	ds_read_b32 v14, v153 offset:5632
	ds_read_b32 v15, v153 offset:5888
	ds_read_b32 v16, v153 offset:6144
	ds_read_b32 v17, v153 offset:6400
	ds_read_b32 v18, v153 offset:6656
	ds_read_b32 v19, v153 offset:6912
	ds_read_b32 v20, v153 offset:7168
	ds_read_b32 v21, v153 offset:7424
	ds_read_b32 v22, v153 offset:7680
	ds_read_b32 v23, v153 offset:7936
	s_waitcnt lgkmcnt(0)
	v_add_f32_e32 v144, v144, v0
	v_add_f32_e32 v145, v145, v1
	v_add_f32_e32 v146, v146, v2
	v_add_f32_e32 v147, v147, v3
	v_add_f32_e32 v148, v148, v4
	v_add_f32_e32 v149, v149, v5
	v_add_f32_e32 v150, v150, v6
	v_add_f32_e32 v151, v151, v7
	v_add_f32_e32 v144, v144, v8
	v_add_f32_e32 v145, v145, v9
	v_add_f32_e32 v146, v146, v10
	v_add_f32_e32 v147, v147, v11
	v_add_f32_e32 v148, v148, v12
	v_add_f32_e32 v149, v149, v13
	v_add_f32_e32 v150, v150, v14
	v_add_f32_e32 v151, v151, v15
	v_add_f32_e32 v144, v144, v16
	v_add_f32_e32 v145, v145, v17
	v_add_f32_e32 v146, v146, v18
	v_add_f32_e32 v147, v147, v19
	v_add_f32_e32 v148, v148, v20
	v_add_f32_e32 v149, v149, v21
	v_add_f32_e32 v150, v150, v22
	v_add_f32_e32 v151, v151, v23
	v_and_b32_e32 v152, 15, v155
	v_lshrrev_b32_e32 v0, 4, v155
	v_lshlrev_b32_e32 v0, 9, v0
	v_lshl_add_u32 v152, v152, 2, v0
	s_lshl_b32 s10, s32, 11
	s_add_u32 s10, s10, 0x1237a100
	s_add_u32 s10, s6, s10
	s_addc_u32 s11, s7, 0
	global_store_dword v152, v144, s[10:11] offset:0
	global_store_dword v152, v145, s[10:11] offset:128
	global_store_dword v152, v146, s[10:11] offset:256
	global_store_dword v152, v147, s[10:11] offset:384
	global_store_dword v152, v148, s[10:11] offset:64
	global_store_dword v152, v149, s[10:11] offset:192
	global_store_dword v152, v150, s[10:11] offset:320
	global_store_dword v152, v151, s[10:11] offset:448
.Ldt2_skip:
	s_or_b64 exec, exec, s[54:55]
	s_barrier
	s_add_u32 s32, s32, s20
	s_branch .Ldt2_rb
.Ldt2_end:
	s_branch .LBB0_204

.LBB0_208:
	s_and_b32 s8, s66, 0xffffff80
	s_ashr_i32 s9, s8, 31
	s_lshl_b32 s7, s68, 11
	s_lshl_b64 s[8:9], s[8:9], 11
	s_and_b32 s20, s7, 0xfc0000
	s_add_i32 s2, s2, s3
	s_cmpk_gt_i32 s2, 0xbff
	s_cselect_b64 s[54:55], -1, 0
	s_lshl_b32 s7, s2, 18
	s_and_b32 s7, s7, 0xfc0000
	s_add_u32 s7, s18, s7
	v_lshl_add_u64 v[126:127], v[114:115], 0, s[8:9]
	s_addc_u32 s10, s19, 0
	s_ashr_i32 s8, s2, 6
	s_ashr_i32 s9, s8, 31
	s_lshl_b64 s[8:9], s[8:9], 18
	v_lshl_add_u64 v[128:129], v[116:117], 0, s[20:21]
	s_add_u32 s20, s16, s8
	s_addc_u32 s11, s17, s9
	s_cmpk_lt_i32 s2, 0xc00
	s_cselect_b64 vcc, -1, 0
	s_and_b64 s[8:9], vcc, exec
	s_cselect_b32 s9, s10, 0
	s_cselect_b32 s8, s7, 0
	v_lshl_add_u64 v[2:3], s[8:9], 0, v[118:119]
	v_lshl_add_u64 v[0:1], v[122:123], 0, s[44:45]
	s_cselect_b32 s11, s11, 0
	s_cselect_b32 s10, s20, 0
	v_lshl_add_u64 v[2:3], v[2:3], 0, v[120:121]
	v_cndmask_b32_e32 v97, v1, v3, vcc
	v_cndmask_b32_e32 v98, v0, v2, vcc
	v_lshl_add_u64 v[0:1], s[10:11], 0, v[118:119]
	v_lshl_add_u64 v[0:1], v[0:1], 0, v[120:121]
	v_lshl_add_u64 v[2:3], v[124:125], 0, s[44:45]
	v_cndmask_b32_e32 v142, v2, v0, vcc
	v_mov_b32_e32 v0, 0
	v_lshl_add_u64 v[144:145], v[122:123], 0, s[28:29]
	v_lshl_add_u64 v[130:131], v[122:123], 0, s[30:31]
	v_lshl_add_u64 v[148:149], v[122:123], 0, s[34:35]
	v_lshl_add_u64 v[132:133], v[122:123], 0, s[36:37]
	v_lshl_add_u64 v[150:151], v[122:123], 0, s[38:39]
	v_lshl_add_u64 v[134:135], v[122:123], 0, s[40:41]
	v_lshl_add_u64 v[152:153], v[122:123], 0, s[42:43]
	v_lshl_add_u64 v[146:147], v[124:125], 0, s[28:29]
	v_lshl_add_u64 v[136:137], v[124:125], 0, s[30:31]
	v_lshl_add_u64 v[154:155], v[124:125], 0, s[34:35]
	v_lshl_add_u64 v[138:139], v[124:125], 0, s[36:37]
	v_lshl_add_u64 v[156:157], v[124:125], 0, s[38:39]
	v_lshl_add_u64 v[140:141], v[124:125], 0, s[40:41]
	v_lshl_add_u64 v[158:159], v[124:125], 0, s[42:43]
	v_cndmask_b32_e32 v143, v3, v1, vcc
	s_mov_b32 s7, -2
	v_mov_b32_e32 v1, v0
	v_mov_b32_e32 v2, v0
	v_mov_b32_e32 v3, v0
	v_mov_b32_e32 v20, v0
	v_mov_b32_e32 v21, v0
	v_mov_b32_e32 v22, v0
	v_mov_b32_e32 v23, v0
	v_mov_b32_e32 v24, v0
	v_mov_b32_e32 v25, v0
	v_mov_b32_e32 v26, v0
	v_mov_b32_e32 v27, v0
	v_mov_b32_e32 v32, v0
	v_mov_b32_e32 v33, v0
	v_mov_b32_e32 v34, v0
	v_mov_b32_e32 v35, v0
	v_mov_b32_e32 v8, v0
	v_mov_b32_e32 v9, v0
	v_mov_b32_e32 v10, v0
	v_mov_b32_e32 v11, v0
	v_mov_b32_e32 v4, v0
	v_mov_b32_e32 v5, v0
	v_mov_b32_e32 v6, v0
	v_mov_b32_e32 v7, v0
	v_mov_b32_e32 v12, v0
	v_mov_b32_e32 v13, v0
	v_mov_b32_e32 v14, v0
	v_mov_b32_e32 v15, v0
	v_mov_b32_e32 v16, v0
	v_mov_b32_e32 v17, v0
	v_mov_b32_e32 v18, v0
	v_mov_b32_e32 v19, v0
	v_mov_b32_e32 v28, v0
	v_mov_b32_e32 v29, v0
	v_mov_b32_e32 v30, v0
	v_mov_b32_e32 v31, v0
	v_mov_b32_e32 v36, v0
	v_mov_b32_e32 v37, v0
	v_mov_b32_e32 v38, v0
	v_mov_b32_e32 v39, v0
	v_mov_b32_e32 v40, v0
	v_mov_b32_e32 v41, v0
	v_mov_b32_e32 v42, v0
	v_mov_b32_e32 v43, v0
	v_mov_b32_e32 v44, v0
	v_mov_b32_e32 v45, v0
	v_mov_b32_e32 v46, v0
	v_mov_b32_e32 v47, v0
	v_mov_b32_e32 v48, v0
	v_mov_b32_e32 v49, v0
	v_mov_b32_e32 v50, v0
	v_mov_b32_e32 v51, v0
	v_mov_b32_e32 v52, v0
	v_mov_b32_e32 v53, v0
	v_mov_b32_e32 v54, v0
	v_mov_b32_e32 v55, v0
	v_mov_b32_e32 v56, v0
	v_mov_b32_e32 v57, v0
	v_mov_b32_e32 v58, v0
	v_mov_b32_e32 v59, v0
	v_mov_b32_e32 v60, v0
	v_mov_b32_e32 v61, v0
	v_mov_b32_e32 v62, v0
	v_mov_b32_e32 v63, v0
	v_readfirstlane_b32 s8, v122
	v_readfirstlane_b32 s9, v123
	v_readfirstlane_b32 s62, v124
	v_readfirstlane_b32 s63, v125
	v_readfirstlane_b32 s7, v247
	s_nop 3
	s_mul_i32 s64, s7, 0x4000
	s_sub_u32 s8, s8, s64
	s_subb_u32 s9, s9, 0
	s_sub_u32 s62, s62, s64
	s_subb_u32 s63, s63, 0
	s_lshl_b32 s7, s7, 12
	s_add_u32 m0, s7, 0x0
	v_mov_b32_e32 v60, 0
	global_load_lds_dwordx4 v248, s[8:9]
	v_mov_b32_e32 v61, 0
	s_add_u32 m0, s7, 0x400
	v_mov_b32_e32 v62, 0
	global_load_lds_dwordx4 v249, s[8:9]
	v_mov_b32_e32 v63, 0
	s_add_u32 m0, s7, 0x800
	v_mov_b32_e32 v56, 0
	global_load_lds_dwordx4 v250, s[8:9]
	v_mov_b32_e32 v57, 0
	s_add_u32 m0, s7, 0xc00
	v_mov_b32_e32 v58, 0
	global_load_lds_dwordx4 v251, s[8:9]
	v_mov_b32_e32 v59, 0
	s_add_u32 m0, s7, 0x8000
	v_mov_b32_e32 v52, 0
	global_load_lds_dwordx4 v248, s[62:63]
	v_mov_b32_e32 v53, 0
	s_add_u32 m0, s7, 0x8400
	v_mov_b32_e32 v54, 0
	global_load_lds_dwordx4 v249, s[62:63]
	v_mov_b32_e32 v55, 0
	s_add_u32 m0, s7, 0x8800
	v_mov_b32_e32 v48, 0
	global_load_lds_dwordx4 v250, s[62:63]
	v_mov_b32_e32 v49, 0
	s_add_u32 m0, s7, 0x8c00
	v_mov_b32_e32 v50, 0
	global_load_lds_dwordx4 v251, s[62:63]
	v_mov_b32_e32 v51, 0
	s_add_u32 s8, s8, 0x80
	s_addc_u32 s9, s9, 0
	s_add_u32 s62, s62, 0x80
	s_addc_u32 s63, s63, 0
	s_add_u32 m0, s7, 0x4000
	v_mov_b32_e32 v44, 0
	global_load_lds_dwordx4 v248, s[8:9]
	v_mov_b32_e32 v45, 0
	s_add_u32 m0, s7, 0x4400
	v_mov_b32_e32 v46, 0
	global_load_lds_dwordx4 v249, s[8:9]
	v_mov_b32_e32 v47, 0
	s_add_u32 m0, s7, 0x4800
	v_mov_b32_e32 v40, 0
	global_load_lds_dwordx4 v250, s[8:9]
	v_mov_b32_e32 v41, 0
	s_add_u32 m0, s7, 0x4c00
	v_mov_b32_e32 v42, 0
	global_load_lds_dwordx4 v251, s[8:9]
	v_mov_b32_e32 v43, 0
	s_add_u32 m0, s7, 0xc000
	v_mov_b32_e32 v36, 0
	global_load_lds_dwordx4 v248, s[62:63]
	v_mov_b32_e32 v37, 0
	s_add_u32 m0, s7, 0xc400
	v_mov_b32_e32 v38, 0
	global_load_lds_dwordx4 v249, s[62:63]
	v_mov_b32_e32 v39, 0
	s_add_u32 m0, s7, 0xc800
	v_mov_b32_e32 v28, 0
	global_load_lds_dwordx4 v250, s[62:63]
	v_mov_b32_e32 v29, 0
	s_add_u32 m0, s7, 0xcc00
	v_mov_b32_e32 v30, 0
	global_load_lds_dwordx4 v251, s[62:63]
	v_mov_b32_e32 v31, 0
	s_add_u32 s8, s8, 0x80
	s_addc_u32 s9, s9, 0
	s_add_u32 s62, s62, 0x80
	s_addc_u32 s63, s63, 0
	v_mov_b32_e32 v16, 0
	v_mov_b32_e32 v17, 0
	v_mov_b32_e32 v18, 0
	v_mov_b32_e32 v19, 0
	v_mov_b32_e32 v12, 0
	v_mov_b32_e32 v13, 0
	v_mov_b32_e32 v14, 0
	v_mov_b32_e32 v15, 0
	v_mov_b32_e32 v4, 0
	v_mov_b32_e32 v5, 0
	v_mov_b32_e32 v6, 0
	v_mov_b32_e32 v7, 0
	v_mov_b32_e32 v8, 0
	v_mov_b32_e32 v9, 0
	v_mov_b32_e32 v10, 0
	v_mov_b32_e32 v11, 0
	v_mov_b32_e32 v32, 0
	v_mov_b32_e32 v33, 0
	v_mov_b32_e32 v34, 0
	v_mov_b32_e32 v35, 0
	v_mov_b32_e32 v24, 0
	v_mov_b32_e32 v25, 0
	v_mov_b32_e32 v26, 0
	v_mov_b32_e32 v27, 0
	v_mov_b32_e32 v20, 0
	v_mov_b32_e32 v21, 0
	v_mov_b32_e32 v22, 0
	v_mov_b32_e32 v23, 0
	v_mov_b32_e32 v0, 0
	v_mov_b32_e32 v1, 0
	v_mov_b32_e32 v2, 0
	v_mov_b32_e32 v3, 0
	s_waitcnt vmcnt(8)
	s_barrier
	ds_read_b128 v[80:83], v252 offset:0
	ds_read_b128 v[144:147], v254 offset:32768
	ds_read_b128 v[148:151], v254 offset:34816
	ds_read_b128 v[152:155], v254 offset:36864
	ds_read_b128 v[156:159], v254 offset:38912
	ds_read_b128 v[84:87], v252 offset:2048
	ds_read_b128 v[88:91], v252 offset:4096
	ds_read_b128 v[92:95], v252 offset:6144
	ds_read_b128 v[124:127], v253 offset:0
	ds_read_b128 v[172:175], v255 offset:32768
	ds_read_b128 v[176:179], v255 offset:34816
	ds_read_b128 v[180:183], v255 offset:36864
	ds_read_b128 v[184:187], v255 offset:38912
	s_waitcnt lgkmcnt(11)
	v_mfma_f32_16x16x32_bf16 v[60:63], v[80:83], v[144:147], v[60:63]
	s_waitcnt lgkmcnt(10)
	v_mfma_f32_16x16x32_bf16 v[56:59], v[80:83], v[148:151], v[56:59]
	s_waitcnt lgkmcnt(9)
	v_mfma_f32_16x16x32_bf16 v[52:55], v[80:83], v[152:155], v[52:55]
	s_waitcnt lgkmcnt(8)
	v_mfma_f32_16x16x32_bf16 v[48:51], v[80:83], v[156:159], v[48:51]
	ds_read_b128 v[132:135], v253 offset:2048
	ds_read_b128 v[136:139], v253 offset:4096
	ds_read_b128 v[140:143], v253 offset:6144
	s_waitcnt lgkmcnt(10)
	v_mfma_f32_16x16x32_bf16 v[44:47], v[84:87], v[144:147], v[44:47]
	v_mfma_f32_16x16x32_bf16 v[40:43], v[84:87], v[148:151], v[40:43]
	v_mfma_f32_16x16x32_bf16 v[36:39], v[84:87], v[152:155], v[36:39]
	v_mfma_f32_16x16x32_bf16 v[28:31], v[84:87], v[156:159], v[28:31]
	s_waitcnt lgkmcnt(0)
	s_barrier
	s_add_u32 m0, s7, 0x0
	v_mfma_f32_16x16x32_bf16 v[16:19], v[88:91], v[144:147], v[16:19]
	global_load_lds_dwordx4 v248, s[8:9]
	s_add_u32 m0, s7, 0x400
	v_mfma_f32_16x16x32_bf16 v[12:15], v[88:91], v[148:151], v[12:15]
	global_load_lds_dwordx4 v249, s[8:9]
	s_add_u32 m0, s7, 0x800
	v_mfma_f32_16x16x32_bf16 v[4:7], v[88:91], v[152:155], v[4:7]
	global_load_lds_dwordx4 v250, s[8:9]
	s_add_u32 m0, s7, 0xc00
	v_mfma_f32_16x16x32_bf16 v[8:11], v[88:91], v[156:159], v[8:11]
	global_load_lds_dwordx4 v251, s[8:9]
	s_add_u32 m0, s7, 0x8000
	v_mfma_f32_16x16x32_bf16 v[32:35], v[92:95], v[144:147], v[32:35]
	global_load_lds_dwordx4 v248, s[62:63]
	s_add_u32 m0, s7, 0x8400
	v_mfma_f32_16x16x32_bf16 v[24:27], v[92:95], v[148:151], v[24:27]
	global_load_lds_dwordx4 v249, s[62:63]
	s_add_u32 m0, s7, 0x8800
	v_mfma_f32_16x16x32_bf16 v[20:23], v[92:95], v[152:155], v[20:23]
	global_load_lds_dwordx4 v250, s[62:63]
	s_add_u32 m0, s7, 0x8c00
	v_mfma_f32_16x16x32_bf16 v[0:3], v[92:95], v[156:159], v[0:3]
	global_load_lds_dwordx4 v251, s[62:63]
	s_add_u32 s8, s8, 0x80
	s_addc_u32 s9, s9, 0
	s_add_u32 s62, s62, 0x80
	s_addc_u32 s63, s63, 0
	s_waitcnt vmcnt(8)
	s_barrier
	ds_read_b128 v[80:83], v252 offset:16384
	ds_read_b128 v[144:147], v254 offset:49152
	ds_read_b128 v[148:151], v254 offset:51200
	ds_read_b128 v[152:155], v254 offset:53248
	ds_read_b128 v[156:159], v254 offset:55296
	ds_read_b128 v[84:87], v252 offset:18432
	ds_read_b128 v[88:91], v252 offset:20480
	ds_read_b128 v[92:95], v252 offset:22528
	v_mfma_f32_16x16x32_bf16 v[60:63], v[124:127], v[172:175], v[60:63]
	v_mfma_f32_16x16x32_bf16 v[56:59], v[124:127], v[176:179], v[56:59]
	v_mfma_f32_16x16x32_bf16 v[52:55], v[124:127], v[180:183], v[52:55]
	v_mfma_f32_16x16x32_bf16 v[48:51], v[124:127], v[184:187], v[48:51]
	v_mfma_f32_16x16x32_bf16 v[44:47], v[132:135], v[172:175], v[44:47]
	v_mfma_f32_16x16x32_bf16 v[40:43], v[132:135], v[176:179], v[40:43]
	v_mfma_f32_16x16x32_bf16 v[36:39], v[132:135], v[180:183], v[36:39]
	v_mfma_f32_16x16x32_bf16 v[28:31], v[132:135], v[184:187], v[28:31]
	v_mfma_f32_16x16x32_bf16 v[16:19], v[136:139], v[172:175], v[16:19]
	v_mfma_f32_16x16x32_bf16 v[12:15], v[136:139], v[176:179], v[12:15]
	v_mfma_f32_16x16x32_bf16 v[4:7], v[136:139], v[180:183], v[4:7]
	v_mfma_f32_16x16x32_bf16 v[8:11], v[136:139], v[184:187], v[8:11]
	v_mfma_f32_16x16x32_bf16 v[32:35], v[140:143], v[172:175], v[32:35]
	v_mfma_f32_16x16x32_bf16 v[24:27], v[140:143], v[176:179], v[24:27]
	v_mfma_f32_16x16x32_bf16 v[20:23], v[140:143], v[180:183], v[20:23]
	v_mfma_f32_16x16x32_bf16 v[0:3], v[140:143], v[184:187], v[0:3]
	ds_read_b128 v[124:127], v253 offset:16384
	ds_read_b128 v[172:175], v255 offset:49152
	ds_read_b128 v[176:179], v255 offset:51200
	ds_read_b128 v[180:183], v255 offset:53248
	ds_read_b128 v[184:187], v255 offset:55296
	ds_read_b128 v[132:135], v253 offset:18432
	ds_read_b128 v[136:139], v253 offset:20480
	ds_read_b128 v[140:143], v253 offset:22528
	s_waitcnt lgkmcnt(14)
	v_mfma_f32_16x16x32_bf16 v[60:63], v[80:83], v[144:147], v[60:63]
	s_waitcnt lgkmcnt(13)
	v_mfma_f32_16x16x32_bf16 v[56:59], v[80:83], v[148:151], v[56:59]
	s_waitcnt lgkmcnt(12)
	v_mfma_f32_16x16x32_bf16 v[52:55], v[80:83], v[152:155], v[52:55]
	s_waitcnt lgkmcnt(11)
	v_mfma_f32_16x16x32_bf16 v[48:51], v[80:83], v[156:159], v[48:51]
	s_waitcnt lgkmcnt(10)
	v_mfma_f32_16x16x32_bf16 v[44:47], v[84:87], v[144:147], v[44:47]
	v_mfma_f32_16x16x32_bf16 v[40:43], v[84:87], v[148:151], v[40:43]
	v_mfma_f32_16x16x32_bf16 v[36:39], v[84:87], v[152:155], v[36:39]
	v_mfma_f32_16x16x32_bf16 v[28:31], v[84:87], v[156:159], v[28:31]
	s_waitcnt lgkmcnt(0)
	s_barrier
	s_add_u32 m0, s7, 0x4000
	v_mfma_f32_16x16x32_bf16 v[16:19], v[88:91], v[144:147], v[16:19]
	global_load_lds_dwordx4 v248, s[8:9]
	s_add_u32 m0, s7, 0x4400
	v_mfma_f32_16x16x32_bf16 v[12:15], v[88:91], v[148:151], v[12:15]
	global_load_lds_dwordx4 v249, s[8:9]
	s_add_u32 m0, s7, 0x4800
	v_mfma_f32_16x16x32_bf16 v[4:7], v[88:91], v[152:155], v[4:7]
	global_load_lds_dwordx4 v250, s[8:9]
	s_add_u32 m0, s7, 0x4c00
	v_mfma_f32_16x16x32_bf16 v[8:11], v[88:91], v[156:159], v[8:11]
	global_load_lds_dwordx4 v251, s[8:9]
	s_add_u32 m0, s7, 0xc000
	v_mfma_f32_16x16x32_bf16 v[32:35], v[92:95], v[144:147], v[32:35]
	global_load_lds_dwordx4 v248, s[62:63]
	s_add_u32 m0, s7, 0xc400
	v_mfma_f32_16x16x32_bf16 v[24:27], v[92:95], v[148:151], v[24:27]
	global_load_lds_dwordx4 v249, s[62:63]
	s_add_u32 m0, s7, 0xc800
	v_mfma_f32_16x16x32_bf16 v[20:23], v[92:95], v[152:155], v[20:23]
	global_load_lds_dwordx4 v250, s[62:63]
	s_add_u32 m0, s7, 0xcc00
	v_mfma_f32_16x16x32_bf16 v[0:3], v[92:95], v[156:159], v[0:3]
	global_load_lds_dwordx4 v251, s[62:63]
	s_add_u32 s8, s8, 0x80
	s_addc_u32 s9, s9, 0
	s_add_u32 s62, s62, 0x80
	s_addc_u32 s63, s63, 0
	s_mov_b32 s32, 6

.LBB0_1573:
	s_cmp_gt_i32 s60, 18
	s_waitcnt lgkmcnt(0)
	s_cselect_b64 s[2:3], -1, 0
	s_cmp_lt_i32 s61, 18
	s_cselect_b64 s[4:5], -1, 0
	s_or_b64 s[2:3], s[2:3], s[4:5]
	s_and_b64 vcc, exec, s[2:3]
	s_cbranch_vccnz .LBB0_1845
	s_mov_b64 s[76:77], s[84:85]
	s_mov_b64 s[14:15], s[0:1]
	s_cmpk_gt_i32 s58, 0xc3f
	s_cbranch_scc1 .LBB0_1791
	s_load_dwordx2 s[16:17], s[14:15], 0xe0
	s_load_dword s3, s[0:1], 0xf0
	v_lshrrev_b32_e32 v9, 3, v162
	v_lshlrev_b32_e32 v0, 3, v162
	v_and_b32_e32 v0, 56, v0
	s_waitcnt lgkmcnt(0)
	s_add_u32 s18, s16, 0x8b7a100
	s_addc_u32 s19, s17, 0
	s_add_u32 s20, s16, 0xc40000
	v_mov_b32_e32 v99, 0
	v_lshlrev_b32_e32 v98, 11, v9
	s_addc_u32 s21, s17, 0
	v_lshl_add_u64 v[4:5], s[18:19], 0, v[98:99]
	v_lshlrev_b32_e32 v6, 1, v0
	v_mov_b32_e32 v7, v99
	v_xor_b32_e32 v10, v163, v162
	v_lshl_add_u64 v[100:101], v[4:5], 0, v[6:7]
	v_lshl_add_u64 v[4:5], s[20:21], 0, v[98:99]
	v_lshl_add_u64 v[102:103], v[4:5], 0, v[6:7]
	v_lshlrev_b32_e32 v5, 4, v10
	v_and_b32_e32 v96, 15, v162
	v_bfe_u32 v4, v162, 1, 3
	v_and_b32_e32 v5, 0x70, v5
	v_bfe_u32 v1, v162, 6, 1
	v_lshrrev_b32_e32 v3, 7, v162
	v_bitop3_b32 v4, v163, v4, 3 bitop3:0x6c
	v_lshl_or_b32 v145, v9, 7, v5
	v_lshlrev_b32_e32 v5, 7, v96
	v_lshl_or_b32 v6, v3, 13, v5
	v_lshl_or_b32 v5, v1, 13, v5
	v_lshlrev_b32_e32 v4, 4, v4
	v_or_b32_e32 v170, v6, v4
	v_or_b32_e32 v171, v5, v4
	v_xor_b32_e32 v4, 64, v4
	v_or_b32_e32 v172, v6, v4
	v_or_b32_e32 v173, v5, v4
	v_lshlrev_b32_e32 v4, 2, v96
	v_mov_b32_e32 v5, v99
	v_lshl_add_u64 v[4:5], s[16:17], 0, v[4:5]
	s_mov_b64 s[6:7], 0x1237a100
	v_lshl_add_u64 v[104:105], v[4:5], 0, s[6:7]
	s_mov_b64 s[6:7], 0x1237a140
	v_lshl_add_u64 v[106:107], v[4:5], 0, s[6:7]
	v_lshlrev_b32_e32 v4, 7, v1
	v_mov_b32_e32 v5, v99
	v_lshl_add_u64 v[4:5], s[16:17], 0, v[4:5]
	s_mov_b64 s[6:7], 0xdb7a100
	s_add_u32 s24, s16, 0xef7a100
	v_lshl_add_u64 v[108:109], v[4:5], 0, s[6:7]
	s_mov_b64 s[6:7], 0xe37a100
	v_lshlrev_b32_e32 v175, 6, v1
	v_cmp_eq_u32_e64 s[4:5], 0, v1
	s_addc_u32 s25, s17, 0
	v_lshl_add_u64 v[110:111], v[4:5], 0, s[6:7]
	v_lshlrev_b32_e32 v4, 1, v96
	v_mov_b32_e32 v5, v99
	v_and_b32_e32 v1, 7, v162
	s_add_u32 s26, s16, 0x6b00000
	v_lshl_add_u64 v[4:5], s[16:17], 0, v[4:5]
	s_mov_b64 s[6:7], 0x9b7a100
	v_lshl_or_b32 v98, v1, 4, v98
	s_addc_u32 s27, s17, 0
	v_lshl_add_u64 v[112:113], v[4:5], 0, s[6:7]
	v_lshl_add_u64 v[4:5], s[16:17], 0, v[98:99]
	s_mov_b64 s[6:7], 0xc40200
	v_bfe_u32 v8, v162, 4, 2
	v_lshlrev_b32_e32 v2, 10, v9
	v_lshlrev_b32_e32 v3, 6, v3
	s_add_u32 s28, s16, 0xcb7a100
	v_lshl_add_u64 v[114:115], v[4:5], 0, s[6:7]
	s_mov_b64 s[6:7], 0x8b7a300
	v_lshl_or_b32 v174, v8, 2, v3
	s_mov_b32 s23, 0
	v_or_b32_e32 v176, v175, v96
	s_addc_u32 s29, s17, 0
	s_lshl_b32 s68, s58, 1
	s_lshl_b32 s69, s3, 1
	v_lshl_add_u64 v[116:117], v[4:5], 0, s[6:7]
	s_lshl_b32 s70, s58, 7
	s_lshl_b32 s71, s3, 7
	s_mov_b64 s[8:9], 0
	s_mov_b32 s73, 0x10000
	s_mov_b64 s[30:31], 0x100
	s_mov_b64 s[34:35], 0x10000
	s_mov_b64 s[36:37], 0x10100
	s_mov_b64 s[38:39], 0x20000
	s_mov_b64 s[40:41], 0x20100
	s_mov_b64 s[42:43], 0x30000
	s_mov_b64 s[44:45], 0x30100
	v_lshlrev_b32_e32 v118, 1, v2
	v_mov_b32_e32 v119, v99
	v_lshlrev_b32_e32 v120, 1, v0
	v_mov_b32_e32 v121, v99
	s_mov_b64 s[46:47], 0x780
	s_brev_b32 s75, 32
	s_mov_b32 s59, 0x3fff80
	s_mov_b32 s78, 0xf786000
	s_mov_b64 s[48:49], 0xf79e500
	s_movk_i32 s79, 0xf400
	s_movk_i32 s80, 0x7e00
	s_mov_b64 s[50:51], 0x2000000
	s_movk_i32 s81, 0xf0
	s_movk_i32 s83, 0x600
	s_movk_i32 s84, 0x200
	s_movk_i32 s85, 0x3d0
	s_movk_i32 s86, 0x3e0
	s_movk_i32 s87, 0x3f0
	s_movk_i32 s88, 0x3c0
	s_mov_b32 s90, 0xab89000
	s_mov_b32 s91, 0xab8a000
	s_mov_b32 s92, 0xab8b000
	s_mov_b32 s93, 0xab8c000
	s_mov_b32 s94, 0xab99000
	s_mov_b32 s95, 0xab9a000
	s_mov_b32 s96, 0xab9b000
	s_mov_b32 s97, 0xab9c000
	s_mov_b32 s89, 0xaba9000
	s_mov_b32 s72, 0xabaa000
	s_mov_b32 s74, 0xabab000
	s_mov_b32 s82, 0xabac000
	s_mov_b64 s[54:55], 0x60
	v_mov_b32_e32 v177, 0x100000
	s_mov_b32 s2, s58
	v_and_b32_e32 v240, 63, v162
	v_lshrrev_b32_e32 v247, 6, v162
	v_lshrrev_b32_e32 v242, 3, v240
	v_lshl_add_u32 v242, v247, 5, v242
	v_and_b32_e32 v243, 7, v240
	v_lshrrev_b32_e32 v244, 4, v240
	v_xor_b32_e32 v243, v243, v244
	v_lshlrev_b32_e32 v243, 4, v243
	v_mov_b32_e32 v241, 0x800
	v_mad_u32_u24 v248, v242, v241, v243
	v_xor_b32_e32 v249, 64, v248
	v_add_u32_e32 v249, 0x4000, v249
	v_add_u32_e32 v250, 0x8000, v248
	v_xor_b32_e32 v251, 64, v248
	v_add_u32_e32 v251, 0xc000, v251
	v_and_b32_e32 v241, 15, v240
	v_lshrrev_b32_e32 v242, 1, v241
	v_xor_b32_e32 v242, v242, v244
	v_lshlrev_b32_e32 v242, 4, v242
	v_lshl_or_b32 v242, v241, 7, v242
	v_lshrrev_b32_e32 v243, 1, v247
	v_lshl_or_b32 v252, v243, 13, v242
	v_xor_b32_e32 v253, 64, v252
	v_and_b32_e32 v243, 1, v247
	v_lshl_or_b32 v254, v243, 13, v242
	v_xor_b32_e32 v255, 64, v254
	s_load_dwordx2 s[6:7], s[0:1], 0xe0
	s_load_dword s22, s[0:1], 0xf0
	v_and_b32_e32 v155, 63, v162
	v_lshrrev_b32_e32 v154, 6, v162
	v_and_b32_e32 v152, 15, v155
	v_lshrrev_b32_e32 v153, 4, v155
	v_lshlrev_b32_e32 v153, 4, v153
	v_lshl_add_u32 v153, v154, 9, v153
	v_lshl_add_u32 v152, v152, 11, v153
	s_waitcnt lgkmcnt(0)
	s_mov_b32 s32, s58
.Ldt18_rb:
	s_cmp_lt_u32 s32, 0x200
	s_cbranch_scc0 .Ldt18_end
	s_lshl_b32 s10, s32, 15
	s_add_u32 s10, s10, 0x8b7a100
	s_add_u32 s10, s6, s10
	s_addc_u32 s11, s7, 0
	s_add_u32 s12, s6, 0x1840000
	s_addc_u32 s13, s7, 0
	global_load_dwordx4 v[0:3], v152, s[10:11] offset:0
	global_load_dwordx4 v[4:7], v152, s[12:13] offset:0
	global_load_dwordx4 v[8:11], v152, s[10:11] offset:64
	global_load_dwordx4 v[12:15], v152, s[12:13] offset:64
	global_load_dwordx4 v[16:19], v152, s[10:11] offset:128
	global_load_dwordx4 v[20:23], v152, s[12:13] offset:128
	global_load_dwordx4 v[24:27], v152, s[10:11] offset:192
	global_load_dwordx4 v[28:31], v152, s[12:13] offset:192
	global_load_dwordx4 v[32:35], v152, s[10:11] offset:256
	global_load_dwordx4 v[36:39], v152, s[12:13] offset:256
	global_load_dwordx4 v[40:43], v152, s[10:11] offset:320
	global_load_dwordx4 v[44:47], v152, s[12:13] offset:320
	global_load_dwordx4 v[48:51], v152, s[10:11] offset:384
	global_load_dwordx4 v[52:55], v152, s[12:13] offset:384
	global_load_dwordx4 v[56:59], v152, s[10:11] offset:448
	global_load_dwordx4 v[60:63], v152, s[12:13] offset:448
	s_add_u32 s12, s12, 0x8000
	s_addc_u32 s13, s13, 0
	global_load_dwordx4 v[80:83], v152, s[12:13] offset:0
	global_load_dwordx4 v[84:87], v152, s[12:13] offset:64
	global_load_dwordx4 v[88:91], v152, s[12:13] offset:128
	global_load_dwordx4 v[92:95], v152, s[12:13] offset:192
	global_load_dwordx4 v[124:127], v152, s[12:13] offset:256
	global_load_dwordx4 v[132:135], v152, s[12:13] offset:320
	global_load_dwordx4 v[136:139], v152, s[12:13] offset:384
	global_load_dwordx4 v[140:143], v152, s[12:13] offset:448
	v_mov_b32_e32 v144, 0
	v_mov_b32_e32 v145, 0
	v_mov_b32_e32 v146, 0
	v_mov_b32_e32 v147, 0
	v_mov_b32_e32 v148, 0
	v_mov_b32_e32 v149, 0
	v_mov_b32_e32 v150, 0
	v_mov_b32_e32 v151, 0
	s_waitcnt vmcnt(22)
	v_mfma_f32_16x16x32_bf16 v[144:147], v[0:3], v[4:7], v[144:147]
	s_waitcnt vmcnt(20)
	v_mfma_f32_16x16x32_bf16 v[144:147], v[8:11], v[12:15], v[144:147]
	s_waitcnt vmcnt(18)
	v_mfma_f32_16x16x32_bf16 v[144:147], v[16:19], v[20:23], v[144:147]
	s_waitcnt vmcnt(16)
	v_mfma_f32_16x16x32_bf16 v[144:147], v[24:27], v[28:31], v[144:147]
	s_waitcnt vmcnt(14)
	v_mfma_f32_16x16x32_bf16 v[144:147], v[32:35], v[36:39], v[144:147]
	s_waitcnt vmcnt(12)
	v_mfma_f32_16x16x32_bf16 v[144:147], v[40:43], v[44:47], v[144:147]
	s_waitcnt vmcnt(10)
	v_mfma_f32_16x16x32_bf16 v[144:147], v[48:51], v[52:55], v[144:147]
	s_waitcnt vmcnt(8)
	v_mfma_f32_16x16x32_bf16 v[144:147], v[56:59], v[60:63], v[144:147]
	s_waitcnt vmcnt(7)
	v_mfma_f32_16x16x32_bf16 v[148:151], v[0:3], v[80:83], v[148:151]
	s_waitcnt vmcnt(6)
	v_mfma_f32_16x16x32_bf16 v[148:151], v[8:11], v[84:87], v[148:151]
	s_waitcnt vmcnt(5)
	v_mfma_f32_16x16x32_bf16 v[148:151], v[16:19], v[88:91], v[148:151]
	s_waitcnt vmcnt(4)
	v_mfma_f32_16x16x32_bf16 v[148:151], v[24:27], v[92:95], v[148:151]
	s_waitcnt vmcnt(3)
	v_mfma_f32_16x16x32_bf16 v[148:151], v[32:35], v[124:127], v[148:151]
	s_waitcnt vmcnt(2)
	v_mfma_f32_16x16x32_bf16 v[148:151], v[40:43], v[132:135], v[148:151]
	s_waitcnt vmcnt(1)
	v_mfma_f32_16x16x32_bf16 v[148:151], v[48:51], v[136:139], v[148:151]
	s_waitcnt vmcnt(0)
	v_mfma_f32_16x16x32_bf16 v[148:151], v[56:59], v[140:143], v[148:151]
	s_nop 7
	s_nop 1
	v_lshlrev_b32_e32 v153, 2, v155
	v_lshl_add_u32 v153, v154, 11, v153
	s_barrier
	ds_write_b32 v153, v144 offset:0
	ds_write_b32 v153, v145 offset:256
	ds_write_b32 v153, v146 offset:512
	ds_write_b32 v153, v147 offset:768
	ds_write_b32 v153, v148 offset:1024
	ds_write_b32 v153, v149 offset:1280
	ds_write_b32 v153, v150 offset:1536
	ds_write_b32 v153, v151 offset:1792
	s_waitcnt lgkmcnt(0)
	s_barrier
	v_cmp_eq_u32_e32 vcc, 0, v154
	s_and_saveexec_b64 s[62:63], vcc
	s_cbranch_execz .Ldt18_skip
	ds_read_b32 v0, v153 offset:2048
	ds_read_b32 v1, v153 offset:2304
	ds_read_b32 v2, v153 offset:2560
	ds_read_b32 v3, v153 offset:2816
	ds_read_b32 v4, v153 offset:3072
	ds_read_b32 v5, v153 offset:3328
	ds_read_b32 v6, v153 offset:3584
	ds_read_b32 v7, v153 offset:3840
	ds_read_b32 v8, v153 offset:4096
	ds_read_b32 v9, v153 offset:4352
	ds_read_b32 v10, v153 offset:4608
	ds_read_b32 v11, v153 offset:4864
	ds_read_b32 v12, v153 offset:5120
	ds_read_b32 v13, v153 offset:5376
	ds_read_b32 v14, v153 offset:5632
	ds_read_b32 v15, v153 offset:5888
	ds_read_b32 v16, v153 offset:6144
	ds_read_b32 v17, v153 offset:6400
	ds_read_b32 v18, v153 offset:6656
	ds_read_b32 v19, v153 offset:6912
	ds_read_b32 v20, v153 offset:7168
	ds_read_b32 v21, v153 offset:7424
	ds_read_b32 v22, v153 offset:7680
	ds_read_b32 v23, v153 offset:7936
	s_waitcnt lgkmcnt(0)
	v_add_f32_e32 v144, v144, v0
	v_add_f32_e32 v145, v145, v1
	v_add_f32_e32 v146, v146, v2
	v_add_f32_e32 v147, v147, v3
	v_add_f32_e32 v148, v148, v4
	v_add_f32_e32 v149, v149, v5
	v_add_f32_e32 v150, v150, v6
	v_add_f32_e32 v151, v151, v7
	v_add_f32_e32 v144, v144, v8
	v_add_f32_e32 v145, v145, v9
	v_add_f32_e32 v146, v146, v10
	v_add_f32_e32 v147, v147, v11
	v_add_f32_e32 v148, v148, v12
	v_add_f32_e32 v149, v149, v13
	v_add_f32_e32 v150, v150, v14
	v_add_f32_e32 v151, v151, v15
	v_add_f32_e32 v144, v144, v16
	v_add_f32_e32 v145, v145, v17
	v_add_f32_e32 v146, v146, v18
	v_add_f32_e32 v147, v147, v19
	v_add_f32_e32 v148, v148, v20
	v_add_f32_e32 v149, v149, v21
	v_add_f32_e32 v150, v150, v22
	v_add_f32_e32 v151, v151, v23
	v_and_b32_e32 v152, 15, v155
	v_lshrrev_b32_e32 v0, 4, v155
	v_lshlrev_b32_e32 v0, 9, v0
	v_lshl_add_u32 v152, v152, 2, v0
	s_lshl_b32 s10, s32, 11
	s_add_u32 s10, s10, 0x1237a100
	s_add_u32 s10, s6, s10
	s_addc_u32 s11, s7, 0
	global_store_dword v152, v144, s[10:11] offset:0
	global_store_dword v152, v145, s[10:11] offset:128
	global_store_dword v152, v146, s[10:11] offset:256
	global_store_dword v152, v147, s[10:11] offset:384
	global_store_dword v152, v148, s[10:11] offset:64
	global_store_dword v152, v149, s[10:11] offset:192
	global_store_dword v152, v150, s[10:11] offset:320
	global_store_dword v152, v151, s[10:11] offset:448
.Ldt18_skip:
	s_or_b64 exec, exec, s[62:63]
	s_barrier
	s_add_u32 s32, s32, s22
	s_branch .Ldt18_rb

.LBB0_1581:
	s_and_b32 s8, s68, 0xffffff80
	s_ashr_i32 s9, s8, 31
	s_lshl_b32 s7, s70, 11
	s_lshl_b64 s[8:9], s[8:9], 11
	s_and_b32 s22, s7, 0xfc0000
	s_add_i32 s2, s2, s3
	s_cmpk_gt_i32 s2, 0xbff
	s_cselect_b64 s[62:63], -1, 0
	s_lshl_b32 s7, s2, 18
	s_and_b32 s7, s7, 0xfc0000
	s_add_u32 s7, s18, s7
	v_lshl_add_u64 v[126:127], v[114:115], 0, s[8:9]
	s_addc_u32 s10, s19, 0
	s_ashr_i32 s8, s2, 6
	s_ashr_i32 s9, s8, 31
	s_lshl_b64 s[8:9], s[8:9], 18
	v_lshl_add_u64 v[130:131], v[116:117], 0, s[22:23]
	s_add_u32 s22, s20, s8
	s_addc_u32 s11, s21, s9
	s_cmpk_lt_i32 s2, 0xc00
	s_cselect_b64 vcc, -1, 0
	s_and_b64 s[8:9], vcc, exec
	s_cselect_b32 s9, s10, 0
	s_cselect_b32 s8, s7, 0
	v_lshl_add_u64 v[2:3], s[8:9], 0, v[118:119]
	v_lshl_add_u64 v[0:1], v[122:123], 0, s[46:47]
	s_cselect_b32 s11, s11, 0
	s_cselect_b32 s10, s22, 0
	v_lshl_add_u64 v[2:3], v[2:3], 0, v[120:121]
	v_cndmask_b32_e32 v97, v1, v3, vcc
	v_cndmask_b32_e32 v98, v0, v2, vcc
	v_lshl_add_u64 v[0:1], s[10:11], 0, v[118:119]
	v_lshl_add_u64 v[0:1], v[0:1], 0, v[120:121]
	v_lshl_add_u64 v[2:3], v[124:125], 0, s[46:47]
	v_cndmask_b32_e32 v144, v2, v0, vcc
	v_mov_b32_e32 v0, 0
	v_lshl_add_u64 v[146:147], v[122:123], 0, s[30:31]
	v_lshl_add_u64 v[132:133], v[122:123], 0, s[34:35]
	v_lshl_add_u64 v[150:151], v[122:123], 0, s[36:37]
	v_lshl_add_u64 v[134:135], v[122:123], 0, s[38:39]
	v_lshl_add_u64 v[152:153], v[122:123], 0, s[40:41]
	v_lshl_add_u64 v[136:137], v[122:123], 0, s[42:43]
	v_lshl_add_u64 v[154:155], v[122:123], 0, s[44:45]
	v_lshl_add_u64 v[148:149], v[124:125], 0, s[30:31]
	v_lshl_add_u64 v[138:139], v[124:125], 0, s[34:35]
	v_lshl_add_u64 v[156:157], v[124:125], 0, s[36:37]
	v_lshl_add_u64 v[140:141], v[124:125], 0, s[38:39]
	v_lshl_add_u64 v[158:159], v[124:125], 0, s[40:41]
	v_lshl_add_u64 v[142:143], v[124:125], 0, s[42:43]
	v_lshl_add_u64 v[160:161], v[124:125], 0, s[44:45]
	v_cndmask_b32_e32 v129, v3, v1, vcc
	s_mov_b32 s7, -2
	v_mov_b32_e32 v1, v0
	v_mov_b32_e32 v2, v0
	v_mov_b32_e32 v3, v0
	v_mov_b32_e32 v20, v0
	v_mov_b32_e32 v21, v0
	v_mov_b32_e32 v22, v0
	v_mov_b32_e32 v23, v0
	v_mov_b32_e32 v24, v0
	v_mov_b32_e32 v25, v0
	v_mov_b32_e32 v26, v0
	v_mov_b32_e32 v27, v0
	v_mov_b32_e32 v32, v0
	v_mov_b32_e32 v33, v0
	v_mov_b32_e32 v34, v0
	v_mov_b32_e32 v35, v0
	v_mov_b32_e32 v8, v0
	v_mov_b32_e32 v9, v0
	v_mov_b32_e32 v10, v0
	v_mov_b32_e32 v11, v0
	v_mov_b32_e32 v4, v0
	v_mov_b32_e32 v5, v0
	v_mov_b32_e32 v6, v0
	v_mov_b32_e32 v7, v0
	v_mov_b32_e32 v12, v0
	v_mov_b32_e32 v13, v0
	v_mov_b32_e32 v14, v0
	v_mov_b32_e32 v15, v0
	v_mov_b32_e32 v16, v0
	v_mov_b32_e32 v17, v0
	v_mov_b32_e32 v18, v0
	v_mov_b32_e32 v19, v0
	v_mov_b32_e32 v28, v0
	v_mov_b32_e32 v29, v0
	v_mov_b32_e32 v30, v0
	v_mov_b32_e32 v31, v0
	v_mov_b32_e32 v36, v0
	v_mov_b32_e32 v37, v0
	v_mov_b32_e32 v38, v0
	v_mov_b32_e32 v39, v0
	v_mov_b32_e32 v40, v0
	v_mov_b32_e32 v41, v0
	v_mov_b32_e32 v42, v0
	v_mov_b32_e32 v43, v0
	v_mov_b32_e32 v44, v0
	v_mov_b32_e32 v45, v0
	v_mov_b32_e32 v46, v0
	v_mov_b32_e32 v47, v0
	v_mov_b32_e32 v48, v0
	v_mov_b32_e32 v49, v0
	v_mov_b32_e32 v50, v0
	v_mov_b32_e32 v51, v0
	v_mov_b32_e32 v52, v0
	v_mov_b32_e32 v53, v0
	v_mov_b32_e32 v54, v0
	v_mov_b32_e32 v55, v0
	v_mov_b32_e32 v56, v0
	v_mov_b32_e32 v57, v0
	v_mov_b32_e32 v58, v0
	v_mov_b32_e32 v59, v0
	v_mov_b32_e32 v60, v0
	v_mov_b32_e32 v61, v0
	v_mov_b32_e32 v62, v0
	v_mov_b32_e32 v63, v0
	v_readfirstlane_b32 s8, v122
	v_readfirstlane_b32 s9, v123
	v_readfirstlane_b32 s64, v124
	v_readfirstlane_b32 s65, v125
	v_readfirstlane_b32 s7, v247
	s_nop 3
	s_mul_i32 s66, s7, 0x4000
	s_sub_u32 s8, s8, s66
	s_subb_u32 s9, s9, 0
	s_sub_u32 s64, s64, s66
	s_subb_u32 s65, s65, 0
	s_lshl_b32 s7, s7, 12
	s_add_u32 m0, s7, 0x0
	v_mov_b32_e32 v60, 0
	global_load_lds_dwordx4 v248, s[8:9]
	v_mov_b32_e32 v61, 0
	s_add_u32 m0, s7, 0x400
	v_mov_b32_e32 v62, 0
	global_load_lds_dwordx4 v249, s[8:9]
	v_mov_b32_e32 v63, 0
	s_add_u32 m0, s7, 0x800
	v_mov_b32_e32 v56, 0
	global_load_lds_dwordx4 v250, s[8:9]
	v_mov_b32_e32 v57, 0
	s_add_u32 m0, s7, 0xc00
	v_mov_b32_e32 v58, 0
	global_load_lds_dwordx4 v251, s[8:9]
	v_mov_b32_e32 v59, 0
	s_add_u32 m0, s7, 0x8000
	v_mov_b32_e32 v52, 0
	global_load_lds_dwordx4 v248, s[64:65]
	v_mov_b32_e32 v53, 0
	s_add_u32 m0, s7, 0x8400
	v_mov_b32_e32 v54, 0
	global_load_lds_dwordx4 v249, s[64:65]
	v_mov_b32_e32 v55, 0
	s_add_u32 m0, s7, 0x8800
	v_mov_b32_e32 v48, 0
	global_load_lds_dwordx4 v250, s[64:65]
	v_mov_b32_e32 v49, 0
	s_add_u32 m0, s7, 0x8c00
	v_mov_b32_e32 v50, 0
	global_load_lds_dwordx4 v251, s[64:65]
	v_mov_b32_e32 v51, 0
	s_add_u32 s8, s8, 0x80
	s_addc_u32 s9, s9, 0
	s_add_u32 s64, s64, 0x80
	s_addc_u32 s65, s65, 0
	s_add_u32 m0, s7, 0x4000
	v_mov_b32_e32 v44, 0
	global_load_lds_dwordx4 v248, s[8:9]
	v_mov_b32_e32 v45, 0
	s_add_u32 m0, s7, 0x4400
	v_mov_b32_e32 v46, 0
	global_load_lds_dwordx4 v249, s[8:9]
	v_mov_b32_e32 v47, 0
	s_add_u32 m0, s7, 0x4800
	v_mov_b32_e32 v40, 0
	global_load_lds_dwordx4 v250, s[8:9]
	v_mov_b32_e32 v41, 0
	s_add_u32 m0, s7, 0x4c00
	v_mov_b32_e32 v42, 0
	global_load_lds_dwordx4 v251, s[8:9]
	v_mov_b32_e32 v43, 0
	s_add_u32 m0, s7, 0xc000
	v_mov_b32_e32 v36, 0
	global_load_lds_dwordx4 v248, s[64:65]
	v_mov_b32_e32 v37, 0
	s_add_u32 m0, s7, 0xc400
	v_mov_b32_e32 v38, 0
	global_load_lds_dwordx4 v249, s[64:65]
	v_mov_b32_e32 v39, 0
	s_add_u32 m0, s7, 0xc800
	v_mov_b32_e32 v28, 0
	global_load_lds_dwordx4 v250, s[64:65]
	v_mov_b32_e32 v29, 0
	s_add_u32 m0, s7, 0xcc00
	v_mov_b32_e32 v30, 0
	global_load_lds_dwordx4 v251, s[64:65]
	v_mov_b32_e32 v31, 0
	s_add_u32 s8, s8, 0x80
	s_addc_u32 s9, s9, 0
	s_add_u32 s64, s64, 0x80
	s_addc_u32 s65, s65, 0
	v_mov_b32_e32 v16, 0
	v_mov_b32_e32 v17, 0
	v_mov_b32_e32 v18, 0
	v_mov_b32_e32 v19, 0
	v_mov_b32_e32 v12, 0
	v_mov_b32_e32 v13, 0
	v_mov_b32_e32 v14, 0
	v_mov_b32_e32 v15, 0
	v_mov_b32_e32 v4, 0
	v_mov_b32_e32 v5, 0
	v_mov_b32_e32 v6, 0
	v_mov_b32_e32 v7, 0
	v_mov_b32_e32 v8, 0
	v_mov_b32_e32 v9, 0
	v_mov_b32_e32 v10, 0
	v_mov_b32_e32 v11, 0
	v_mov_b32_e32 v32, 0
	v_mov_b32_e32 v33, 0
	v_mov_b32_e32 v34, 0
	v_mov_b32_e32 v35, 0
	v_mov_b32_e32 v24, 0
	v_mov_b32_e32 v25, 0
	v_mov_b32_e32 v26, 0
	v_mov_b32_e32 v27, 0
	v_mov_b32_e32 v20, 0
	v_mov_b32_e32 v21, 0
	v_mov_b32_e32 v22, 0
	v_mov_b32_e32 v23, 0
	v_mov_b32_e32 v0, 0
	v_mov_b32_e32 v1, 0
	v_mov_b32_e32 v2, 0
	v_mov_b32_e32 v3, 0
	s_waitcnt vmcnt(8)
	s_barrier
	ds_read_b128 v[80:83], v252 offset:0
	ds_read_b128 v[144:147], v254 offset:32768
	ds_read_b128 v[148:151], v254 offset:34816
	ds_read_b128 v[152:155], v254 offset:36864
	ds_read_b128 v[156:159], v254 offset:38912
	ds_read_b128 v[84:87], v252 offset:2048
	ds_read_b128 v[88:91], v252 offset:4096
	ds_read_b128 v[92:95], v252 offset:6144
	ds_read_b128 v[124:127], v253 offset:0
	ds_read_b128 v[180:183], v255 offset:32768
	ds_read_b128 v[184:187], v255 offset:34816
	ds_read_b128 v[188:191], v255 offset:36864
	ds_read_b128 v[192:195], v255 offset:38912
	s_waitcnt lgkmcnt(11)
	v_mfma_f32_16x16x32_bf16 v[60:63], v[80:83], v[144:147], v[60:63]
	s_waitcnt lgkmcnt(10)
	v_mfma_f32_16x16x32_bf16 v[56:59], v[80:83], v[148:151], v[56:59]
	s_waitcnt lgkmcnt(9)
	v_mfma_f32_16x16x32_bf16 v[52:55], v[80:83], v[152:155], v[52:55]
	s_waitcnt lgkmcnt(8)
	v_mfma_f32_16x16x32_bf16 v[48:51], v[80:83], v[156:159], v[48:51]
	ds_read_b128 v[132:135], v253 offset:2048
	ds_read_b128 v[136:139], v253 offset:4096
	ds_read_b128 v[140:143], v253 offset:6144
	s_waitcnt lgkmcnt(10)
	v_mfma_f32_16x16x32_bf16 v[44:47], v[84:87], v[144:147], v[44:47]
	v_mfma_f32_16x16x32_bf16 v[40:43], v[84:87], v[148:151], v[40:43]
	v_mfma_f32_16x16x32_bf16 v[36:39], v[84:87], v[152:155], v[36:39]
	v_mfma_f32_16x16x32_bf16 v[28:31], v[84:87], v[156:159], v[28:31]
	s_waitcnt lgkmcnt(0)
	s_barrier
	s_add_u32 m0, s7, 0x0
	v_mfma_f32_16x16x32_bf16 v[16:19], v[88:91], v[144:147], v[16:19]
	global_load_lds_dwordx4 v248, s[8:9]
	s_add_u32 m0, s7, 0x400
	v_mfma_f32_16x16x32_bf16 v[12:15], v[88:91], v[148:151], v[12:15]
	global_load_lds_dwordx4 v249, s[8:9]
	s_add_u32 m0, s7, 0x800
	v_mfma_f32_16x16x32_bf16 v[4:7], v[88:91], v[152:155], v[4:7]
	global_load_lds_dwordx4 v250, s[8:9]
	s_add_u32 m0, s7, 0xc00
	v_mfma_f32_16x16x32_bf16 v[8:11], v[88:91], v[156:159], v[8:11]
	global_load_lds_dwordx4 v251, s[8:9]
	s_add_u32 m0, s7, 0x8000
	v_mfma_f32_16x16x32_bf16 v[32:35], v[92:95], v[144:147], v[32:35]
	global_load_lds_dwordx4 v248, s[64:65]
	s_add_u32 m0, s7, 0x8400
	v_mfma_f32_16x16x32_bf16 v[24:27], v[92:95], v[148:151], v[24:27]
	global_load_lds_dwordx4 v249, s[64:65]
	s_add_u32 m0, s7, 0x8800
	v_mfma_f32_16x16x32_bf16 v[20:23], v[92:95], v[152:155], v[20:23]
	global_load_lds_dwordx4 v250, s[64:65]
	s_add_u32 m0, s7, 0x8c00
	v_mfma_f32_16x16x32_bf16 v[0:3], v[92:95], v[156:159], v[0:3]
	global_load_lds_dwordx4 v251, s[64:65]
	s_add_u32 s8, s8, 0x80
	s_addc_u32 s9, s9, 0
	s_add_u32 s64, s64, 0x80
	s_addc_u32 s65, s65, 0
	s_waitcnt vmcnt(8)
	s_barrier
	ds_read_b128 v[80:83], v252 offset:16384
	ds_read_b128 v[144:147], v254 offset:49152
	ds_read_b128 v[148:151], v254 offset:51200
	ds_read_b128 v[152:155], v254 offset:53248
	ds_read_b128 v[156:159], v254 offset:55296
	ds_read_b128 v[84:87], v252 offset:18432
	ds_read_b128 v[88:91], v252 offset:20480
	ds_read_b128 v[92:95], v252 offset:22528
	v_mfma_f32_16x16x32_bf16 v[60:63], v[124:127], v[180:183], v[60:63]
	v_mfma_f32_16x16x32_bf16 v[56:59], v[124:127], v[184:187], v[56:59]
	v_mfma_f32_16x16x32_bf16 v[52:55], v[124:127], v[188:191], v[52:55]
	v_mfma_f32_16x16x32_bf16 v[48:51], v[124:127], v[192:195], v[48:51]
	v_mfma_f32_16x16x32_bf16 v[44:47], v[132:135], v[180:183], v[44:47]
	v_mfma_f32_16x16x32_bf16 v[40:43], v[132:135], v[184:187], v[40:43]
	v_mfma_f32_16x16x32_bf16 v[36:39], v[132:135], v[188:191], v[36:39]
	v_mfma_f32_16x16x32_bf16 v[28:31], v[132:135], v[192:195], v[28:31]
	v_mfma_f32_16x16x32_bf16 v[16:19], v[136:139], v[180:183], v[16:19]
	v_mfma_f32_16x16x32_bf16 v[12:15], v[136:139], v[184:187], v[12:15]
	v_mfma_f32_16x16x32_bf16 v[4:7], v[136:139], v[188:191], v[4:7]
	v_mfma_f32_16x16x32_bf16 v[8:11], v[136:139], v[192:195], v[8:11]
	v_mfma_f32_16x16x32_bf16 v[32:35], v[140:143], v[180:183], v[32:35]
	v_mfma_f32_16x16x32_bf16 v[24:27], v[140:143], v[184:187], v[24:27]
	v_mfma_f32_16x16x32_bf16 v[20:23], v[140:143], v[188:191], v[20:23]
	v_mfma_f32_16x16x32_bf16 v[0:3], v[140:143], v[192:195], v[0:3]
	ds_read_b128 v[124:127], v253 offset:16384
	ds_read_b128 v[180:183], v255 offset:49152
	ds_read_b128 v[184:187], v255 offset:51200
	ds_read_b128 v[188:191], v255 offset:53248
	ds_read_b128 v[192:195], v255 offset:55296
	ds_read_b128 v[132:135], v253 offset:18432
	ds_read_b128 v[136:139], v253 offset:20480
	ds_read_b128 v[140:143], v253 offset:22528
	s_waitcnt lgkmcnt(14)
	v_mfma_f32_16x16x32_bf16 v[60:63], v[80:83], v[144:147], v[60:63]
	s_waitcnt lgkmcnt(13)
	v_mfma_f32_16x16x32_bf16 v[56:59], v[80:83], v[148:151], v[56:59]
	s_waitcnt lgkmcnt(12)
	v_mfma_f32_16x16x32_bf16 v[52:55], v[80:83], v[152:155], v[52:55]
	s_waitcnt lgkmcnt(11)
	v_mfma_f32_16x16x32_bf16 v[48:51], v[80:83], v[156:159], v[48:51]
	s_waitcnt lgkmcnt(10)
	v_mfma_f32_16x16x32_bf16 v[44:47], v[84:87], v[144:147], v[44:47]
	v_mfma_f32_16x16x32_bf16 v[40:43], v[84:87], v[148:151], v[40:43]
	v_mfma_f32_16x16x32_bf16 v[36:39], v[84:87], v[152:155], v[36:39]
	v_mfma_f32_16x16x32_bf16 v[28:31], v[84:87], v[156:159], v[28:31]
	s_waitcnt lgkmcnt(0)
	s_barrier
	s_add_u32 m0, s7, 0x4000
	v_mfma_f32_16x16x32_bf16 v[16:19], v[88:91], v[144:147], v[16:19]
	global_load_lds_dwordx4 v248, s[8:9]
	s_add_u32 m0, s7, 0x4400
	v_mfma_f32_16x16x32_bf16 v[12:15], v[88:91], v[148:151], v[12:15]
	global_load_lds_dwordx4 v249, s[8:9]
	s_add_u32 m0, s7, 0x4800
	v_mfma_f32_16x16x32_bf16 v[4:7], v[88:91], v[152:155], v[4:7]
	global_load_lds_dwordx4 v250, s[8:9]
	s_add_u32 m0, s7, 0x4c00
	v_mfma_f32_16x16x32_bf16 v[8:11], v[88:91], v[156:159], v[8:11]
	global_load_lds_dwordx4 v251, s[8:9]
	s_add_u32 m0, s7, 0xc000
	v_mfma_f32_16x16x32_bf16 v[32:35], v[92:95], v[144:147], v[32:35]
	global_load_lds_dwordx4 v248, s[64:65]
	s_add_u32 m0, s7, 0xc400
	v_mfma_f32_16x16x32_bf16 v[24:27], v[92:95], v[148:151], v[24:27]
	global_load_lds_dwordx4 v249, s[64:65]
	s_add_u32 m0, s7, 0xc800
	v_mfma_f32_16x16x32_bf16 v[20:23], v[92:95], v[152:155], v[20:23]
	global_load_lds_dwordx4 v250, s[64:65]
	s_add_u32 m0, s7, 0xcc00
	v_mfma_f32_16x16x32_bf16 v[0:3], v[92:95], v[156:159], v[0:3]
	global_load_lds_dwordx4 v251, s[64:65]
	s_add_u32 s8, s8, 0x80
	s_addc_u32 s9, s9, 0
	s_add_u32 s64, s64, 0x80
	s_addc_u32 s65, s65, 0
	s_mov_b32 s32, 6
